# attention softmax: mask-free copy of the section selected by a wave-uniform branch when the key tile needs no window mask
# baseline (speedup 1.0000x reference)
.LBB0_1654:
	v_add_u32_e32 v100, v157, v147
	ds_read_b128 v[80:83], v100
	ds_read_b128 v[96:99], v100 offset:64
	ds_read_b128 v[84:87], v100 offset:4352
	ds_read_b128 v[88:91], v100 offset:8704
	ds_read_b128 v[92:95], v100 offset:13056
	s_waitcnt lgkmcnt(4)
	v_mfma_f32_16x16x32_bf16 v[80:83], v[8:11], v[80:83], 0
	s_or_b32 s14, s31, 16
	s_or_b32 s15, s31, 32
	s_or_b32 s16, s31, 48
	s_waitcnt lgkmcnt(3)
	v_mfma_f32_16x16x32_bf16 v[80:83], v[0:3], v[96:99], v[80:83]
	ds_read_b128 v[96:99], v100 offset:4416
	s_add_i32 s9, s9, 64
	s_waitcnt lgkmcnt(3)
	v_mfma_f32_16x16x32_bf16 v[84:87], v[8:11], v[84:87], 0
	s_waitcnt lgkmcnt(0)
	v_mfma_f32_16x16x32_bf16 v[84:87], v[0:3], v[96:99], v[84:87]
	ds_read_b128 v[96:99], v100 offset:8768
	v_mfma_f32_16x16x32_bf16 v[88:91], v[8:11], v[88:91], 0
	s_waitcnt lgkmcnt(0)
	v_mfma_f32_16x16x32_bf16 v[88:91], v[0:3], v[96:99], v[88:91]
	ds_read_b128 v[96:99], v100 offset:13120
	v_mfma_f32_16x16x32_bf16 v[92:95], v[8:11], v[92:95], 0
	s_waitcnt lgkmcnt(0)
	v_mfma_f32_16x16x32_bf16 v[92:95], v[0:3], v[96:99], v[92:95]
	ds_read_b128 v[96:99], v100 offset:128
	s_waitcnt lgkmcnt(0)
	v_mfma_f32_16x16x32_bf16 v[80:83], v[4:7], v[96:99], v[80:83]
	ds_read_b128 v[96:99], v100 offset:4480
	s_waitcnt lgkmcnt(0)
	v_mfma_f32_16x16x32_bf16 v[84:87], v[4:7], v[96:99], v[84:87]
	ds_read_b128 v[96:99], v100 offset:8832
	s_waitcnt lgkmcnt(0)
	v_mfma_f32_16x16x32_bf16 v[88:91], v[4:7], v[96:99], v[88:91]
	ds_read_b128 v[96:99], v100 offset:13184
	s_waitcnt lgkmcnt(0)
	v_mfma_f32_16x16x32_bf16 v[92:95], v[4:7], v[96:99], v[92:95]
	ds_read_b128 v[96:99], v100 offset:192
	s_waitcnt lgkmcnt(0)
	v_mfma_f32_16x16x32_bf16 v[80:83], v[12:15], v[96:99], v[80:83]
	ds_read_b128 v[96:99], v100 offset:4544
	s_waitcnt lgkmcnt(0)
	v_mfma_f32_16x16x32_bf16 v[84:87], v[12:15], v[96:99], v[84:87]
	ds_read_b128 v[96:99], v100 offset:8896
	s_nop 3
	v_mul_f32_e32 v80, 0x3db504f3, v80
	s_waitcnt lgkmcnt(0)
	v_mfma_f32_16x16x32_bf16 v[88:91], v[12:15], v[96:99], v[88:91]
	ds_read_b128 v[96:99], v100 offset:13248
	v_mul_f32_e32 v84, 0x3db504f3, v84
	s_waitcnt lgkmcnt(0)
	v_mfma_f32_16x16x32_bf16 v[92:95], v[12:15], v[96:99], v[92:95]
	s_and_b64 vcc, exec, s[12:13]
	s_cbranch_vccz .Latt_nomask
	v_subrev_u32_e32 v96, s31, v175
	v_cmp_gt_u32_e32 vcc, s24, v96
	s_and_b64 vcc, s[12:13], vcc
	v_subrev_u32_e32 v96, s14, v175
	v_cndmask_b32_e32 v80, v80, v173, vcc
	v_cmp_gt_u32_e32 vcc, s24, v96
	s_and_b64 vcc, s[12:13], vcc
	v_subrev_u32_e32 v97, s15, v175
	v_cndmask_b32_e32 v84, v84, v173, vcc
	v_cmp_gt_u32_e32 vcc, s24, v97
	v_mul_f32_e32 v88, 0x3db504f3, v88
	s_and_b64 vcc, s[12:13], vcc
	v_subrev_u32_e32 v97, s16, v175
	v_cndmask_b32_e32 v88, v88, v173, vcc
	v_cmp_gt_u32_e32 vcc, s24, v97
	v_mul_f32_e32 v92, 0x3db504f3, v92
	s_and_b64 vcc, s[12:13], vcc
	v_max3_f32 v96, v80, s25, v84
	v_cndmask_b32_e32 v92, v92, v173, vcc
	v_max3_f32 v96, v96, v88, v92
	s_nop 1
	v_mov_b32_dpp v97, v96 quad_perm:[1,0,3,2] row_mask:0xf bank_mask:0xf bound_ctrl:1
	v_max_f32_e32 v97, v97, v97
	v_max_f32_e32 v96, v96, v97
	s_nop 1
	v_mov_b32_dpp v97, v96 quad_perm:[2,3,0,1] row_mask:0xf bank_mask:0xf bound_ctrl:1
	v_max_f32_e32 v97, v97, v97
	v_max_f32_e32 v96, v96, v97
	s_nop 1
	v_mov_b32_dpp v97, v96 row_half_mirror row_mask:0xf bank_mask:0xf bound_ctrl:1
	v_max_f32_e32 v97, v97, v97
	v_max_f32_e32 v96, v96, v97
	s_nop 1
	v_mov_b32_dpp v97, v96 row_mirror row_mask:0xf bank_mask:0xf bound_ctrl:1
	v_max3_f32 v137, v141, v96, v97
	v_sub_f32_e32 v80, v80, v137
	v_mul_f32_e32 v80, 0x3fb8aa3b, v80
	v_exp_f32_e32 v99, v80
	v_sub_f32_e32 v96, v141, v137
	v_mul_f32_e32 v96, 0x3fb8aa3b, v96
	v_exp_f32_e32 v97, v96
	v_cvt_pk_bf16_f32 v80, v99, s0
	ds_write_b16 v171, v80 offset:35840
	v_sub_f32_e32 v80, v84, v137
	v_mul_f32_e32 v80, 0x3fb8aa3b, v80
	v_exp_f32_e32 v101, v80
	v_subrev_u32_e32 v84, s14, v176
	v_mov_b32_e32 v184, v97
	v_cvt_pk_bf16_f32 v80, v101, s0
	ds_write_b16 v171, v80 offset:35872
	v_sub_f32_e32 v80, v88, v137
	v_mul_f32_e32 v80, 0x3fb8aa3b, v80
	v_exp_f32_e32 v103, v80
	v_subrev_u32_e32 v88, s15, v176
	v_cvt_pk_bf16_f32 v80, v103, s0
	ds_write_b16 v171, v80 offset:35904
	v_sub_f32_e32 v80, v92, v137
	v_mul_f32_e32 v80, 0x3fb8aa3b, v80
	v_exp_f32_e32 v141, v80
	s_nop 0
	v_cvt_pk_bf16_f32 v80, v141, s0
	ds_write_b16 v171, v80 offset:35936
	v_mul_f32_e32 v80, 0x3db504f3, v81
	v_subrev_u32_e32 v81, s31, v176
	v_cmp_gt_u32_e32 vcc, s24, v81
	s_and_b64 vcc, s[12:13], vcc
	v_mul_f32_e32 v81, 0x3db504f3, v85
	v_cndmask_b32_e32 v80, v80, v173, vcc
	v_cmp_gt_u32_e32 vcc, s24, v84
	s_and_b64 vcc, s[12:13], vcc
	v_mul_f32_e32 v85, 0x3db504f3, v89
	v_cndmask_b32_e32 v81, v81, v173, vcc
	v_cmp_gt_u32_e32 vcc, s24, v88
	s_and_b64 vcc, s[12:13], vcc
	v_subrev_u32_e32 v89, s16, v176
	v_cndmask_b32_e32 v85, v85, v173, vcc
	v_cmp_gt_u32_e32 vcc, s24, v89
	v_mul_f32_e32 v88, 0x3db504f3, v93
	s_and_b64 vcc, s[12:13], vcc
	v_max3_f32 v84, v80, s25, v81
	v_cndmask_b32_e32 v88, v88, v173, vcc
	v_max3_f32 v84, v84, v85, v88
	s_nop 1
	v_mov_b32_dpp v89, v84 quad_perm:[1,0,3,2] row_mask:0xf bank_mask:0xf bound_ctrl:1
	v_max_f32_e32 v89, v89, v89
	v_max_f32_e32 v84, v84, v89
	s_nop 1
	v_mov_b32_dpp v89, v84 quad_perm:[2,3,0,1] row_mask:0xf bank_mask:0xf bound_ctrl:1
	v_max_f32_e32 v89, v89, v89
	v_max_f32_e32 v84, v84, v89
	s_nop 1
	v_mov_b32_dpp v89, v84 row_half_mirror row_mask:0xf bank_mask:0xf bound_ctrl:1
	v_max_f32_e32 v89, v89, v89
	v_max_f32_e32 v84, v84, v89
	s_nop 1
	v_mov_b32_dpp v89, v84 row_mirror row_mask:0xf bank_mask:0xf bound_ctrl:1
	v_max3_f32 v135, v140, v84, v89
	v_sub_f32_e32 v80, v80, v135
	v_mul_f32_e32 v80, 0x3fb8aa3b, v80
	v_exp_f32_e32 v98, v80
	v_sub_f32_e32 v84, v140, v135
	v_mul_f32_e32 v84, 0x3fb8aa3b, v84
	v_exp_f32_e32 v96, v84
	v_cvt_pk_bf16_f32 v80, v98, s0
	ds_write_b16 v171, v80 offset:35984
	v_sub_f32_e32 v80, v81, v135
	v_mul_f32_e32 v80, 0x3fb8aa3b, v80
	v_exp_f32_e32 v100, v80
	v_mov_b32_e32 v185, v96
	v_pk_mul_f32 v[92:93], v[16:17], v[184:185]
	v_pk_mul_f32 v[16:17], v[40:41], v[184:185]
	v_cvt_pk_bf16_f32 v80, v100, s0
	ds_write_b16 v171, v80 offset:36016
	v_sub_f32_e32 v80, v85, v135
	v_mul_f32_e32 v80, 0x3fb8aa3b, v80
	v_exp_f32_e32 v102, v80
	v_pk_fma_f32 v[80:81], v[120:121], v[96:97], v[98:99]
	v_subrev_u32_e32 v85, s15, v177
	v_pk_add_f32 v[80:81], v[100:101], v[80:81]
	v_cvt_pk_bf16_f32 v84, v102, s0
	ds_write_b16 v171, v84 offset:36048
	v_sub_f32_e32 v84, v88, v135
	v_mul_f32_e32 v84, 0x3fb8aa3b, v84
	v_exp_f32_e32 v140, v84
	v_pk_add_f32 v[80:81], v[102:103], v[80:81]
	v_mul_f32_e32 v84, 0x3db504f3, v90
	v_pk_mul_f32 v[88:89], v[20:21], v[184:185]
	v_pk_add_f32 v[120:121], v[140:141], v[80:81]
	v_subrev_u32_e32 v81, s31, v177
	v_cvt_pk_bf16_f32 v80, v140, s0
	v_cmp_gt_u32_e32 vcc, s24, v81
	ds_write_b16 v171, v80 offset:36080
	v_mul_f32_e32 v80, 0x3db504f3, v82
	s_and_b64 vcc, s[12:13], vcc
	v_subrev_u32_e32 v82, s14, v177
	v_cndmask_b32_e32 v80, v80, v173, vcc
	v_cmp_gt_u32_e32 vcc, s24, v82
	v_mul_f32_e32 v81, 0x3db504f3, v86
	s_and_b64 vcc, s[12:13], vcc
	v_cndmask_b32_e32 v81, v81, v173, vcc
	v_cmp_gt_u32_e32 vcc, s24, v85
	s_and_b64 vcc, s[12:13], vcc
	v_subrev_u32_e32 v86, s16, v177
	v_cndmask_b32_e32 v84, v84, v173, vcc
	v_cmp_gt_u32_e32 vcc, s24, v86
	v_mul_f32_e32 v85, 0x3db504f3, v94
	s_and_b64 vcc, s[12:13], vcc
	v_max3_f32 v82, v80, s25, v81
	v_cndmask_b32_e32 v85, v85, v173, vcc
	v_max3_f32 v82, v82, v84, v85
	v_pk_mul_f32 v[20:21], v[44:45], v[184:185]
	s_nop 0
	v_mov_b32_dpp v86, v82 quad_perm:[1,0,3,2] row_mask:0xf bank_mask:0xf bound_ctrl:1
	v_max_f32_e32 v86, v86, v86
	v_max_f32_e32 v82, v82, v86
	s_nop 1
	v_mov_b32_dpp v86, v82 quad_perm:[2,3,0,1] row_mask:0xf bank_mask:0xf bound_ctrl:1
	v_max_f32_e32 v86, v86, v86
	v_max_f32_e32 v82, v82, v86
	s_nop 1
	v_mov_b32_dpp v86, v82 row_half_mirror row_mask:0xf bank_mask:0xf bound_ctrl:1
	v_max_f32_e32 v86, v86, v86
	v_max_f32_e32 v82, v82, v86
	s_nop 1
	v_mov_b32_dpp v86, v82 row_mirror row_mask:0xf bank_mask:0xf bound_ctrl:1
	v_max3_f32 v131, v139, v82, v86
	v_sub_f32_e32 v80, v80, v131
	v_mul_f32_e32 v80, 0x3fb8aa3b, v80
	v_exp_f32_e32 v103, v80
	v_sub_f32_e32 v82, v139, v131
	v_mul_f32_e32 v82, 0x3fb8aa3b, v82
	v_exp_f32_e32 v98, v82
	v_cvt_pk_bf16_f32 v80, v103, s0
	ds_write_b16 v171, v80 offset:36128
	v_sub_f32_e32 v80, v81, v131
	v_mul_f32_e32 v80, 0x3fb8aa3b, v80
	v_exp_f32_e32 v139, v80
	v_subrev_u32_e32 v81, s31, v178
	v_cmp_gt_u32_e32 vcc, s24, v81
	s_and_b64 vcc, s[12:13], vcc
	v_cvt_pk_bf16_f32 v80, v139, s0
	ds_write_b16 v171, v80 offset:36160
	v_sub_f32_e32 v80, v84, v131
	v_mul_f32_e32 v80, 0x3fb8aa3b, v80
	v_exp_f32_e32 v141, v80
	v_subrev_u32_e32 v81, s14, v178
	v_subrev_u32_e32 v82, s15, v178
	v_cvt_pk_bf16_f32 v80, v141, s0
	ds_write_b16 v171, v80 offset:36192
	v_sub_f32_e32 v80, v85, v131
	v_mul_f32_e32 v80, 0x3fb8aa3b, v80
	v_exp_f32_e32 v101, v80
	v_pk_mul_f32 v[84:85], v[24:25], v[184:185]
	v_pk_mul_f32 v[24:25], v[36:37], v[184:185]
	v_cvt_pk_bf16_f32 v80, v101, s0
	ds_write_b16 v171, v80 offset:36224
	v_mul_f32_e32 v80, 0x3db504f3, v83
	v_cndmask_b32_e32 v100, v80, v173, vcc
	v_cmp_gt_u32_e32 vcc, s24, v81
	v_mul_f32_e32 v80, 0x3db504f3, v87
	s_and_b64 vcc, s[12:13], vcc
	v_cndmask_b32_e32 v140, v80, v173, vcc
	v_cmp_gt_u32_e32 vcc, s24, v82
	v_mul_f32_e32 v81, 0x3db504f3, v91
	s_and_b64 vcc, s[12:13], vcc
	v_subrev_u32_e32 v82, s16, v178
	v_cndmask_b32_e32 v183, v81, v173, vcc
	v_cmp_gt_u32_e32 vcc, s24, v82
	v_mul_f32_e32 v81, 0x3db504f3, v95
	s_and_b64 vcc, s[12:13], vcc
	v_max3_f32 v80, v100, s25, v140
	v_cndmask_b32_e32 v186, v81, v173, vcc
	v_max3_f32 v80, v80, v183, v186
	s_cmp_lg_u32 s28, s11
	s_nop 0
	v_mov_b32_dpp v81, v80 quad_perm:[1,0,3,2] row_mask:0xf bank_mask:0xf bound_ctrl:1
	v_max_f32_e32 v81, v81, v81
	v_max_f32_e32 v80, v80, v81
	s_nop 1
	v_mov_b32_dpp v81, v80 quad_perm:[2,3,0,1] row_mask:0xf bank_mask:0xf bound_ctrl:1
	v_max_f32_e32 v81, v81, v81
	v_max_f32_e32 v80, v80, v81
	s_nop 1
	v_mov_b32_dpp v81, v80 row_half_mirror row_mask:0xf bank_mask:0xf bound_ctrl:1
	v_max_f32_e32 v81, v81, v81
	v_max_f32_e32 v80, v80, v81
	s_nop 1
	v_mov_b32_dpp v81, v80 row_mirror row_mask:0xf bank_mask:0xf bound_ctrl:1
	v_max3_f32 v133, v138, v80, v81
	v_sub_f32_e32 v80, v138, v133
	v_mul_f32_e32 v80, 0x3fb8aa3b, v80
	v_exp_f32_e32 v99, v80
	v_pk_mul_f32 v[80:81], v[28:29], v[184:185]
	v_pk_mul_f32 v[28:29], v[32:33], v[184:185]
	v_sub_f32_e32 v32, v100, v133
	v_mul_f32_e32 v32, 0x3fb8aa3b, v32
	v_exp_f32_e32 v102, v32
	v_pk_mul_f32 v[82:83], v[30:31], v[98:99]
	v_pk_mul_f32 v[30:31], v[34:35], v[98:99]
	v_mov_b32_e32 v33, v98
	v_cvt_pk_bf16_f32 v32, v102, s0
	ds_write_b16 v171, v32 offset:36272
	v_sub_f32_e32 v32, v140, v133
	v_mul_f32_e32 v32, 0x3fb8aa3b, v32
	v_exp_f32_e32 v138, v32
	v_pk_mul_f32 v[90:91], v[22:23], v[98:99]
	v_pk_mul_f32 v[22:23], v[46:47], v[98:99]
	v_pk_mul_f32 v[86:87], v[26:27], v[98:99]
	v_cvt_pk_bf16_f32 v32, v138, s0
	ds_write_b16 v171, v32 offset:36304
	v_sub_f32_e32 v32, v183, v133
	v_mul_f32_e32 v32, 0x3fb8aa3b, v32
	v_exp_f32_e32 v140, v32
	v_mov_b32_e32 v32, v99
	v_pk_fma_f32 v[32:33], v[118:119], v[32:33], v[102:103]
	v_pk_mul_f32 v[26:27], v[38:39], v[98:99]
	v_cvt_pk_bf16_f32 v34, v140, s0
	ds_write_b16 v171, v34 offset:36336
	v_sub_f32_e32 v34, v186, v133
	v_mul_f32_e32 v34, 0x3fb8aa3b, v34
	v_exp_f32_e32 v100, v34
	v_pk_add_f32 v[32:33], v[138:139], v[32:33]
	v_add_u32_e32 v138, v157, v158
	v_pk_add_f32 v[32:33], v[140:141], v[32:33]
	v_pk_mul_f32 v[94:95], v[18:19], v[98:99]
	v_pk_add_f32 v[118:119], v[100:101], v[32:33]
	v_cvt_pk_bf16_f32 v32, v100, s0
	ds_write_b16 v171, v32 offset:36368
	s_branch .Latt_join
.Latt_nomask:
	s_nop 7
	s_nop 7
	s_nop 7
	v_mul_f32_e32 v88, 0x3db504f3, v88
	v_mul_f32_e32 v92, 0x3db504f3, v92
	v_max3_f32 v96, v80, s25, v84
	v_max3_f32 v96, v96, v88, v92
	s_nop 1
	s_nop 1
	v_mov_b32_dpp v97, v96 quad_perm:[1,0,3,2] row_mask:0xf bank_mask:0xf bound_ctrl:1
	v_max_f32_e32 v97, v97, v97
	v_max_f32_e32 v96, v96, v97
	s_nop 1
	s_nop 1
	v_mov_b32_dpp v97, v96 quad_perm:[2,3,0,1] row_mask:0xf bank_mask:0xf bound_ctrl:1
	v_max_f32_e32 v97, v97, v97
	v_max_f32_e32 v96, v96, v97
	s_nop 1
	s_nop 1
	v_mov_b32_dpp v97, v96 row_half_mirror row_mask:0xf bank_mask:0xf bound_ctrl:1
	v_max_f32_e32 v97, v97, v97
	v_max_f32_e32 v96, v96, v97
	s_nop 1
	s_nop 1
	v_mov_b32_dpp v97, v96 row_mirror row_mask:0xf bank_mask:0xf bound_ctrl:1
	v_max3_f32 v137, v141, v96, v97
	v_sub_f32_e32 v80, v80, v137
	v_mul_f32_e32 v80, 0x3fb8aa3b, v80
	v_exp_f32_e32 v99, v80
	s_nop 0
	v_sub_f32_e32 v96, v141, v137
	v_mul_f32_e32 v96, 0x3fb8aa3b, v96
	v_exp_f32_e32 v97, v96
	s_nop 0
	v_cvt_pk_bf16_f32 v80, v99, s0
	ds_write_b16 v171, v80 offset:35840
	v_sub_f32_e32 v80, v84, v137
	v_mul_f32_e32 v80, 0x3fb8aa3b, v80
	v_exp_f32_e32 v101, v80
	s_nop 0
	v_mov_b32_e32 v184, v97
	v_cvt_pk_bf16_f32 v80, v101, s0
	ds_write_b16 v171, v80 offset:35872
	v_sub_f32_e32 v80, v88, v137
	v_mul_f32_e32 v80, 0x3fb8aa3b, v80
	v_exp_f32_e32 v103, v80
	s_nop 0
	v_cvt_pk_bf16_f32 v80, v103, s0
	ds_write_b16 v171, v80 offset:35904
	v_sub_f32_e32 v80, v92, v137
	v_mul_f32_e32 v80, 0x3fb8aa3b, v80
	v_exp_f32_e32 v141, v80
	s_nop 0
	s_nop 0
	v_cvt_pk_bf16_f32 v80, v141, s0
	ds_write_b16 v171, v80 offset:35936
	v_mul_f32_e32 v80, 0x3db504f3, v81
	v_mul_f32_e32 v81, 0x3db504f3, v85
	v_mul_f32_e32 v85, 0x3db504f3, v89
	v_mul_f32_e32 v88, 0x3db504f3, v93
	v_max3_f32 v84, v80, s25, v81
	v_max3_f32 v84, v84, v85, v88
	s_nop 1
	s_nop 1
	v_mov_b32_dpp v89, v84 quad_perm:[1,0,3,2] row_mask:0xf bank_mask:0xf bound_ctrl:1
	v_max_f32_e32 v89, v89, v89
	v_max_f32_e32 v84, v84, v89
	s_nop 1
	s_nop 1
	v_mov_b32_dpp v89, v84 quad_perm:[2,3,0,1] row_mask:0xf bank_mask:0xf bound_ctrl:1
	v_max_f32_e32 v89, v89, v89
	v_max_f32_e32 v84, v84, v89
	s_nop 1
	s_nop 1
	v_mov_b32_dpp v89, v84 row_half_mirror row_mask:0xf bank_mask:0xf bound_ctrl:1
	v_max_f32_e32 v89, v89, v89
	v_max_f32_e32 v84, v84, v89
	s_nop 1
	s_nop 1
	v_mov_b32_dpp v89, v84 row_mirror row_mask:0xf bank_mask:0xf bound_ctrl:1
	v_max3_f32 v135, v140, v84, v89
	v_sub_f32_e32 v80, v80, v135
	v_mul_f32_e32 v80, 0x3fb8aa3b, v80
	v_exp_f32_e32 v98, v80
	s_nop 0
	v_sub_f32_e32 v84, v140, v135
	v_mul_f32_e32 v84, 0x3fb8aa3b, v84
	v_exp_f32_e32 v96, v84
	s_nop 0
	v_cvt_pk_bf16_f32 v80, v98, s0
	ds_write_b16 v171, v80 offset:35984
	v_sub_f32_e32 v80, v81, v135
	v_mul_f32_e32 v80, 0x3fb8aa3b, v80
	v_exp_f32_e32 v100, v80
	s_nop 0
	v_mov_b32_e32 v185, v96
	v_pk_mul_f32 v[92:93], v[16:17], v[184:185]
	v_pk_mul_f32 v[16:17], v[40:41], v[184:185]
	v_cvt_pk_bf16_f32 v80, v100, s0
	ds_write_b16 v171, v80 offset:36016
	v_sub_f32_e32 v80, v85, v135
	v_mul_f32_e32 v80, 0x3fb8aa3b, v80
	v_exp_f32_e32 v102, v80
	s_nop 0
	v_pk_fma_f32 v[80:81], v[120:121], v[96:97], v[98:99]
	v_pk_add_f32 v[80:81], v[100:101], v[80:81]
	v_cvt_pk_bf16_f32 v84, v102, s0
	ds_write_b16 v171, v84 offset:36048
	v_sub_f32_e32 v84, v88, v135
	v_mul_f32_e32 v84, 0x3fb8aa3b, v84
	v_exp_f32_e32 v140, v84
	s_nop 0
	v_pk_add_f32 v[80:81], v[102:103], v[80:81]
	v_mul_f32_e32 v84, 0x3db504f3, v90
	v_pk_mul_f32 v[88:89], v[20:21], v[184:185]
	v_pk_add_f32 v[120:121], v[140:141], v[80:81]
	v_cvt_pk_bf16_f32 v80, v140, s0
	ds_write_b16 v171, v80 offset:36080
	v_mul_f32_e32 v80, 0x3db504f3, v82
	v_mul_f32_e32 v81, 0x3db504f3, v86
	v_mul_f32_e32 v85, 0x3db504f3, v94
	v_max3_f32 v82, v80, s25, v81
	v_max3_f32 v82, v82, v84, v85
	v_pk_mul_f32 v[20:21], v[44:45], v[184:185]
	s_nop 0
	s_nop 1
	v_mov_b32_dpp v86, v82 quad_perm:[1,0,3,2] row_mask:0xf bank_mask:0xf bound_ctrl:1
	v_max_f32_e32 v86, v86, v86
	v_max_f32_e32 v82, v82, v86
	s_nop 1
	s_nop 1
	v_mov_b32_dpp v86, v82 quad_perm:[2,3,0,1] row_mask:0xf bank_mask:0xf bound_ctrl:1
	v_max_f32_e32 v86, v86, v86
	v_max_f32_e32 v82, v82, v86
	s_nop 1
	s_nop 1
	v_mov_b32_dpp v86, v82 row_half_mirror row_mask:0xf bank_mask:0xf bound_ctrl:1
	v_max_f32_e32 v86, v86, v86
	v_max_f32_e32 v82, v82, v86
	s_nop 1
	s_nop 1
	v_mov_b32_dpp v86, v82 row_mirror row_mask:0xf bank_mask:0xf bound_ctrl:1
	v_max3_f32 v131, v139, v82, v86
	v_sub_f32_e32 v80, v80, v131
	v_mul_f32_e32 v80, 0x3fb8aa3b, v80
	v_exp_f32_e32 v103, v80
	s_nop 0
	v_sub_f32_e32 v82, v139, v131
	v_mul_f32_e32 v82, 0x3fb8aa3b, v82
	v_exp_f32_e32 v98, v82
	s_nop 0
	v_cvt_pk_bf16_f32 v80, v103, s0
	ds_write_b16 v171, v80 offset:36128
	v_sub_f32_e32 v80, v81, v131
	v_mul_f32_e32 v80, 0x3fb8aa3b, v80
	v_exp_f32_e32 v139, v80
	s_nop 0
	v_cvt_pk_bf16_f32 v80, v139, s0
	ds_write_b16 v171, v80 offset:36160
	v_sub_f32_e32 v80, v84, v131
	v_mul_f32_e32 v80, 0x3fb8aa3b, v80
	v_exp_f32_e32 v141, v80
	s_nop 0
	v_cvt_pk_bf16_f32 v80, v141, s0
	ds_write_b16 v171, v80 offset:36192
	v_sub_f32_e32 v80, v85, v131
	v_mul_f32_e32 v80, 0x3fb8aa3b, v80
	v_exp_f32_e32 v101, v80
	s_nop 0
	v_pk_mul_f32 v[84:85], v[24:25], v[184:185]
	v_pk_mul_f32 v[24:25], v[36:37], v[184:185]
	v_cvt_pk_bf16_f32 v80, v101, s0
	ds_write_b16 v171, v80 offset:36224
	v_mul_f32_e32 v80, 0x3db504f3, v83
	v_mov_b32_e32 v100, v80
	v_mul_f32_e32 v80, 0x3db504f3, v87
	v_mov_b32_e32 v140, v80
	v_mul_f32_e32 v81, 0x3db504f3, v91
	v_mov_b32_e32 v183, v81
	v_mul_f32_e32 v81, 0x3db504f3, v95
	v_max3_f32 v80, v100, s25, v140
	v_mov_b32_e32 v186, v81
	v_max3_f32 v80, v80, v183, v186
	s_cmp_lg_u32 s28, s11
	s_nop 0
	s_nop 1
	v_mov_b32_dpp v81, v80 quad_perm:[1,0,3,2] row_mask:0xf bank_mask:0xf bound_ctrl:1
	v_max_f32_e32 v81, v81, v81
	v_max_f32_e32 v80, v80, v81
	s_nop 1
	s_nop 1
	v_mov_b32_dpp v81, v80 quad_perm:[2,3,0,1] row_mask:0xf bank_mask:0xf bound_ctrl:1
	v_max_f32_e32 v81, v81, v81
	v_max_f32_e32 v80, v80, v81
	s_nop 1
	s_nop 1
	v_mov_b32_dpp v81, v80 row_half_mirror row_mask:0xf bank_mask:0xf bound_ctrl:1
	v_max_f32_e32 v81, v81, v81
	v_max_f32_e32 v80, v80, v81
	s_nop 1
	s_nop 1
	v_mov_b32_dpp v81, v80 row_mirror row_mask:0xf bank_mask:0xf bound_ctrl:1
	v_max3_f32 v133, v138, v80, v81
	v_sub_f32_e32 v80, v138, v133
	v_mul_f32_e32 v80, 0x3fb8aa3b, v80
	v_exp_f32_e32 v99, v80
	s_nop 0
	v_pk_mul_f32 v[80:81], v[28:29], v[184:185]
	v_pk_mul_f32 v[28:29], v[32:33], v[184:185]
	v_sub_f32_e32 v32, v100, v133
	v_mul_f32_e32 v32, 0x3fb8aa3b, v32
	v_exp_f32_e32 v102, v32
	s_nop 0
	v_pk_mul_f32 v[82:83], v[30:31], v[98:99]
	v_pk_mul_f32 v[30:31], v[34:35], v[98:99]
	v_mov_b32_e32 v33, v98
	v_cvt_pk_bf16_f32 v32, v102, s0
	ds_write_b16 v171, v32 offset:36272
	v_sub_f32_e32 v32, v140, v133
	v_mul_f32_e32 v32, 0x3fb8aa3b, v32
	v_exp_f32_e32 v138, v32
	s_nop 0
	v_pk_mul_f32 v[90:91], v[22:23], v[98:99]
	v_pk_mul_f32 v[22:23], v[46:47], v[98:99]
	v_pk_mul_f32 v[86:87], v[26:27], v[98:99]
	v_cvt_pk_bf16_f32 v32, v138, s0
	ds_write_b16 v171, v32 offset:36304
	v_sub_f32_e32 v32, v183, v133
	v_mul_f32_e32 v32, 0x3fb8aa3b, v32
	v_exp_f32_e32 v140, v32
	s_nop 0
	v_mov_b32_e32 v32, v99
	v_pk_fma_f32 v[32:33], v[118:119], v[32:33], v[102:103]
	v_pk_mul_f32 v[26:27], v[38:39], v[98:99]
	v_cvt_pk_bf16_f32 v34, v140, s0
	ds_write_b16 v171, v34 offset:36336
	v_sub_f32_e32 v34, v186, v133
	v_mul_f32_e32 v34, 0x3fb8aa3b, v34
	v_exp_f32_e32 v100, v34
	s_nop 0
	v_pk_add_f32 v[32:33], v[138:139], v[32:33]
	v_add_u32_e32 v138, v157, v158
	v_pk_add_f32 v[32:33], v[140:141], v[32:33]
	v_pk_mul_f32 v[94:95], v[18:19], v[98:99]
	v_pk_add_f32 v[118:119], v[100:101], v[32:33]
	v_cvt_pk_bf16_f32 v32, v100, s0
	ds_write_b16 v171, v32 offset:36368
.Latt_join:
	s_waitcnt lgkmcnt(0)
	s_barrier
	ds_read_b128 v[32:35], v159 offset:35840
	ds_read_b128 v[44:47], v172 offset:19712
	s_waitcnt lgkmcnt(0)
	v_mfma_f32_16x16x32_bf16 v[44:47], v[32:35], v[44:47], v[84:87]
	s_nop 2
	ds_read_b128 v[84:87], v172 offset:22016
	ds_read_b128 v[36:39], v138 offset:17408
	v_pk_mul_f32 v[18:19], v[42:43], v[98:99]
	s_waitcnt lgkmcnt(1)
	v_mfma_f32_16x16x32_bf16 v[80:83], v[32:35], v[84:87], v[80:83]
	ds_read_b128 v[84:87], v138 offset:26624
	ds_read_b128 v[40:43], v172 offset:17408
	s_waitcnt lgkmcnt(1)
	v_mfma_f32_16x16x32_bf16 v[84:87], v[32:35], v[84:87], v[28:31]
	s_nop 2
	ds_read_b128 v[28:31], v138 offset:28928
	s_waitcnt lgkmcnt(1)
	v_mfma_f32_16x16x32_bf16 v[40:43], v[32:35], v[40:43], v[88:91]
	s_waitcnt lgkmcnt(0)
	v_mfma_f32_16x16x32_bf16 v[88:91], v[32:35], v[28:31], v[24:27]
	s_nop 2
	ds_read_b128 v[24:27], v138 offset:31232
	v_mfma_f32_16x16x32_bf16 v[36:39], v[32:35], v[36:39], v[92:95]
	s_waitcnt lgkmcnt(0)
	v_mfma_f32_16x16x32_bf16 v[92:95], v[32:35], v[24:27], v[20:23]
	s_nop 2
	ds_read_b128 v[20:23], v138 offset:33536
	s_waitcnt lgkmcnt(0)
	v_mfma_f32_16x16x32_bf16 v[96:99], v[32:35], v[20:23], v[16:19]
	ds_read_b128 v[100:103], v159 offset:35904
	s_nop 1
	ds_read_b128 v[16:19], v138 offset:17472
	ds_read_b128 v[20:23], v172 offset:17472
	ds_read_b128 v[24:27], v172 offset:19776
	s_waitcnt lgkmcnt(2)
	v_mfma_f32_16x16x32_bf16 v[16:19], v[100:103], v[16:19], v[36:39]
	ds_read_b128 v[28:31], v172 offset:22080
	s_nop 1
	ds_read_b128 v[36:39], v138 offset:28992
	ds_read_b128 v[32:35], v138 offset:26688
	s_waitcnt lgkmcnt(4)
	v_mfma_f32_16x16x32_bf16 v[20:23], v[100:103], v[20:23], v[40:43]
	s_nop 2
	ds_read_b128 v[40:43], v138 offset:31296
	s_waitcnt lgkmcnt(4)
	v_mfma_f32_16x16x32_bf16 v[24:27], v[100:103], v[24:27], v[44:47]
	s_waitcnt lgkmcnt(0)
	v_mfma_f32_16x16x32_bf16 v[44:47], v[100:103], v[40:43], v[92:95]
	ds_read_b128 v[40:43], v138 offset:33600
	v_mfma_f32_16x16x32_bf16 v[28:31], v[100:103], v[28:31], v[80:83]
	v_mfma_f32_16x16x32_bf16 v[32:35], v[100:103], v[32:35], v[84:87]
	v_mfma_f32_16x16x32_bf16 v[36:39], v[100:103], v[36:39], v[88:91]
	s_waitcnt lgkmcnt(0)
	v_mfma_f32_16x16x32_bf16 v[40:43], v[100:103], v[40:43], v[96:99]
	s_cbranch_scc0 .LBB0_1637
	v_mov_b32_e32 v138, v133
	v_mov_b32_e32 v139, v131
	v_mov_b32_e32 v140, v135
	v_mov_b32_e32 v141, v137
	s_branch .LBB0_1642
